# item-C bias addresses computed once per loop iteration; 20 more canonicalise v_max removed; dead v_mov removed
# speedup vs baseline: 1.0117x; 1.0020x over previous
; __device__ __forceinline__ float qmax(float x) { float a = x, b = x; swap16(a, b); a = fmaxf(a, b); b = a; swap32(a, b); return fmaxf(a, b); }
; __device__ __forceinline__ void softmax_pv(float& m, float& l, f32x4 (&o)[4], f32x4 s0, f32x4 s1, const bf16x8 (&vf)[4], float kL2e) {
;     float mx = fmaxf(fmaxf(fmaxf(s0[0], s0[1]), fmaxf(s0[2], s0[3])), fmaxf(fmaxf(s1[0], s1[1]), fmaxf(s1[2], s1[3])));
;     mx = qmax(mx);
;     const float mn = fmaxf(m, mx);
;     if (__builtin_amdgcn_ballot_w64(mn > m) != 0ull) {
;         const float alpha = __builtin_amdgcn_exp2f((m - mn) * kL2e);
;         l *= alpha;
; #pragma unroll
;         for (int dt = 0; dt < 4; ++dt) o[dt] = o[dt] * alpha;
;         m = mn;
.LBB0_368:
	v_max_f32_e32 v156, v2, v204
	v_max_f32_e32 v157, v214, v215
	v_max_f32_e32 v3, v216, v3
	v_max3_f32 v3, v210, v212, v3
	v_max3_f32 v3, v156, v157, v3
	v_mov_b32_e32 v156, v3
	s_nop 1
	v_permlane16_swap_b32 v3, v156
	s_nop 1
	s_nop 0
	v_max_f32_e32 v3, v3, v156
	v_mov_b32_e32 v156, v3
	s_nop 1
	v_permlane32_swap_b32 v3, v156
	s_nop 1
	s_nop 0
	v_max3_f32 v179, v0, v3, v156
	v_cmp_gt_f32_e32 vcc, v179, v0
	s_cbranch_vccz .LBB0_370
	v_sub_f32_e32 v0, v0, v179
	v_mul_f32_e32 v0, v174, v0
	v_exp_f32_e32 v0, v0
	s_nop 0
	v_mul_f32_e32 v192, v192, v0
	v_pk_mul_f32 v[94:95], v[94:95], v[0:1] op_sel_hi:[1,0]
	v_pk_mul_f32 v[92:93], v[92:93], v[0:1] op_sel_hi:[1,0]
	v_pk_mul_f32 v[98:99], v[98:99], v[0:1] op_sel_hi:[1,0]
	v_pk_mul_f32 v[96:97], v[96:97], v[0:1] op_sel_hi:[1,0]
	v_pk_mul_f32 v[90:91], v[90:91], v[0:1] op_sel_hi:[1,0]
	v_pk_mul_f32 v[88:89], v[88:89], v[0:1] op_sel_hi:[1,0]
	v_pk_mul_f32 v[86:87], v[86:87], v[0:1] op_sel_hi:[1,0]
	v_pk_mul_f32 v[84:85], v[84:85], v[0:1] op_sel_hi:[1,0]
	s_branch .LBB0_371

; __device__ __forceinline__ float qmax(float x) { float a = x, b = x; swap16(a, b); a = fmaxf(a, b); b = a; swap32(a, b); return fmaxf(a, b); }
; __device__ __forceinline__ void softmax_pv(float& m, float& l, f32x4 (&o)[4], f32x4 s0, f32x4 s1, const bf16x8 (&vf)[4], float kL2e) {
;     float mx = fmaxf(fmaxf(fmaxf(s0[0], s0[1]), fmaxf(s0[2], s0[3])), fmaxf(fmaxf(s1[0], s1[1]), fmaxf(s1[2], s1[3])));
;     mx = qmax(mx);
;     const float mn = fmaxf(m, mx);
;     if (__builtin_amdgcn_ballot_w64(mn > m) != 0ull) {
;         const float alpha = __builtin_amdgcn_exp2f((m - mn) * kL2e);
;         l *= alpha;
; #pragma unroll
;         for (int dt = 0; dt < 4; ++dt) o[dt] = o[dt] * alpha;
;         m = mn;
.LBB0_375:
	v_max_f32_e32 v2, v217, v217
	s_nop 2
	v_max_f32_e32 v156, v0, v0
	v_max_f32_e32 v2, v156, v2
	v_max_f32_e32 v156, v219, v221
	v_max_f32_e32 v3, v220, v3
	v_max3_f32 v3, v216, v218, v3
	v_max3_f32 v2, v2, v156, v3
	v_mov_b32_e32 v3, v2
	s_nop 1
	v_permlane16_swap_b32 v2, v3
	s_nop 1
	s_nop 0
	v_max_f32_e32 v2, v2, v3
	v_mov_b32_e32 v3, v2
	s_nop 1
	v_permlane32_swap_b32 v2, v3
	s_nop 1
	s_nop 0
	v_max3_f32 v3, v201, v2, v3
	v_cmp_gt_f32_e32 vcc, v3, v201
	s_cbranch_vccz .LBB0_377
	v_sub_f32_e32 v2, v201, v3
	v_mul_f32_e32 v2, v174, v2
	v_exp_f32_e32 v2, v2
	s_nop 0
	v_mul_f32_e32 v190, v190, v2
	v_pk_mul_f32 v[82:83], v[82:83], v[2:3] op_sel_hi:[1,0]
	v_pk_mul_f32 v[80:81], v[80:81], v[2:3] op_sel_hi:[1,0]
	v_pk_mul_f32 v[78:79], v[78:79], v[2:3] op_sel_hi:[1,0]
	v_pk_mul_f32 v[76:77], v[76:77], v[2:3] op_sel_hi:[1,0]
	v_pk_mul_f32 v[74:75], v[74:75], v[2:3] op_sel_hi:[1,0]
	v_pk_mul_f32 v[72:73], v[72:73], v[2:3] op_sel_hi:[1,0]
	v_pk_mul_f32 v[70:71], v[70:71], v[2:3] op_sel_hi:[1,0]
	v_pk_mul_f32 v[68:69], v[68:69], v[2:3] op_sel_hi:[1,0]
	s_branch .LBB0_378

; __device__ __forceinline__ float qmax(float x) { float a = x, b = x; swap16(a, b); a = fmaxf(a, b); b = a; swap32(a, b); return fmaxf(a, b); }
; __device__ __forceinline__ void softmax_pv(float& m, float& l, f32x4 (&o)[4], f32x4 s0, f32x4 s1, const bf16x8 (&vf)[4], float kL2e) {
;     float mx = fmaxf(fmaxf(fmaxf(s0[0], s0[1]), fmaxf(s0[2], s0[3])), fmaxf(fmaxf(s1[0], s1[1]), fmaxf(s1[2], s1[3])));
;     mx = qmax(mx);
;     const float mn = fmaxf(m, mx);
;     if (__builtin_amdgcn_ballot_w64(mn > m) != 0ull) {
;         const float alpha = __builtin_amdgcn_exp2f((m - mn) * kL2e);
;         l *= alpha;
; #pragma unroll
;         for (int dt = 0; dt < 4; ++dt) o[dt] = o[dt] * alpha;
;         m = mn;
.LBB0_382:
	v_max_f32_e32 v0, v0, v153
	v_max_f32_e32 v101, v155, v164
	v_max_f32_e32 v102, v163, v165
	v_max3_f32 v102, v152, v154, v102
	v_max3_f32 v0, v0, v101, v102
	v_mov_b32_e32 v101, v0
	s_nop 1
	v_permlane16_swap_b32 v0, v101
	s_nop 1
	s_nop 0
	v_max_f32_e32 v0, v0, v101
	v_mov_b32_e32 v101, v0
	s_nop 1
	v_permlane32_swap_b32 v0, v101
	s_nop 1
	s_nop 0
	v_max3_f32 v101, v199, v0, v101
	v_cmp_gt_f32_e32 vcc, v101, v199
	s_cbranch_vccz .LBB0_384
	v_sub_f32_e32 v0, v199, v101
	v_mul_f32_e32 v0, v174, v0
	v_exp_f32_e32 v0, v0
	s_nop 0
	v_mul_f32_e32 v177, v177, v0
	v_pk_mul_f32 v[66:67], v[66:67], v[0:1] op_sel_hi:[1,0]
	v_pk_mul_f32 v[64:65], v[64:65], v[0:1] op_sel_hi:[1,0]
	v_pk_mul_f32 v[62:63], v[62:63], v[0:1] op_sel_hi:[1,0]
	v_pk_mul_f32 v[60:61], v[60:61], v[0:1] op_sel_hi:[1,0]
	v_pk_mul_f32 v[58:59], v[58:59], v[0:1] op_sel_hi:[1,0]
	v_pk_mul_f32 v[56:57], v[56:57], v[0:1] op_sel_hi:[1,0]
	v_pk_mul_f32 v[54:55], v[54:55], v[0:1] op_sel_hi:[1,0]
	v_pk_mul_f32 v[52:53], v[52:53], v[0:1] op_sel_hi:[1,0]
	s_branch .LBB0_385

; __device__ __forceinline__ float qmax(float x) { float a = x, b = x; swap16(a, b); a = fmaxf(a, b); b = a; swap32(a, b); return fmaxf(a, b); }
; __device__ __forceinline__ void softmax_pv(float& m, float& l, f32x4 (&o)[4], f32x4 s0, f32x4 s1, const bf16x8 (&vf)[4], float kL2e) {
;     float mx = fmaxf(fmaxf(fmaxf(s0[0], s0[1]), fmaxf(s0[2], s0[3])), fmaxf(fmaxf(s1[0], s1[1]), fmaxf(s1[2], s1[3])));
;     mx = qmax(mx);
;     const float mn = fmaxf(m, mx);
;     if (__builtin_amdgcn_ballot_w64(mn > m) != 0ull) {
;         const float alpha = __builtin_amdgcn_exp2f((m - mn) * kL2e);
;         l *= alpha;
; #pragma unroll
;         for (int dt = 0; dt < 4; ++dt) o[dt] = o[dt] * alpha;
;         m = mn;
.LBB0_420:
	v_max_f32_e32 v0, v0, v117
	v_max_f32_e32 v93, v119, v125
	v_max_f32_e32 v94, v124, v126
	v_max3_f32 v94, v113, v118, v94
	v_max3_f32 v0, v0, v93, v94
	v_mov_b32_e32 v93, v0
	s_nop 1
	v_permlane16_swap_b32 v0, v93
	s_nop 1
	s_nop 0
	v_max_f32_e32 v0, v0, v93
	v_mov_b32_e32 v93, v0
	s_nop 1
	v_permlane32_swap_b32 v0, v93
	s_nop 1
	s_nop 0
	v_max3_f32 v93, v136, v0, v93
	v_cmp_gt_f32_e32 vcc, v93, v136
	s_cbranch_vccz .LBB0_422
	v_sub_f32_e32 v0, v136, v93
	v_mul_f32_e32 v0, v130, v0
	v_exp_f32_e32 v0, v0
	v_mov_b32_e32 v136, v93
	v_mul_f32_e32 v138, v138, v0
	v_pk_mul_f32 v[18:19], v[18:19], v[0:1] op_sel_hi:[1,0]
	v_pk_mul_f32 v[16:17], v[16:17], v[0:1] op_sel_hi:[1,0]
	v_pk_mul_f32 v[14:15], v[14:15], v[0:1] op_sel_hi:[1,0]
	v_pk_mul_f32 v[12:13], v[12:13], v[0:1] op_sel_hi:[1,0]
	v_pk_mul_f32 v[10:11], v[10:11], v[0:1] op_sel_hi:[1,0]
	v_pk_mul_f32 v[8:9], v[8:9], v[0:1] op_sel_hi:[1,0]
	v_pk_mul_f32 v[6:7], v[6:7], v[0:1] op_sel_hi:[1,0]
	v_pk_mul_f32 v[4:5], v[4:5], v[0:1] op_sel_hi:[1,0]
	s_branch .LBB0_423

; __device__ __forceinline__ float qmax(float x) { float a = x, b = x; swap16(a, b); a = fmaxf(a, b); b = a; swap32(a, b); return fmaxf(a, b); }
; __device__ __forceinline__ void softmax_pv(float& m, float& l, f32x4 (&o)[4], f32x4 s0, f32x4 s1, const bf16x8 (&vf)[4], float kL2e) {
;     float mx = fmaxf(fmaxf(fmaxf(s0[0], s0[1]), fmaxf(s0[2], s0[3])), fmaxf(fmaxf(s1[0], s1[1]), fmaxf(s1[2], s1[3])));
;     mx = qmax(mx);
;     const float mn = fmaxf(m, mx);
;     if (__builtin_amdgcn_ballot_w64(mn > m) != 0ull) {
;         const float alpha = __builtin_amdgcn_exp2f((m - mn) * kL2e);
;         l *= alpha;
; #pragma unroll
;         for (int dt = 0; dt < 4; ++dt) o[dt] = o[dt] * alpha;
;         m = mn;
.LBB0_428:
	v_max_f32_e32 v0, v0, v89
	v_max_f32_e32 v77, v91, v94
	v_max_f32_e32 v78, v93, v95
	v_max3_f32 v78, v88, v90, v78
	v_max3_f32 v0, v0, v77, v78
	v_mov_b32_e32 v77, v0
	s_nop 1
	v_permlane16_swap_b32 v0, v77
	s_nop 1
	s_nop 0
	v_max_f32_e32 v0, v0, v77
	v_mov_b32_e32 v77, v0
	s_nop 1
	v_permlane32_swap_b32 v0, v77
	s_nop 1
	s_nop 0
	v_max3_f32 v77, v136, v0, v77
	v_cmp_gt_f32_e32 vcc, v77, v136
	s_cbranch_vccz .LBB0_430
	v_sub_f32_e32 v0, v136, v77
	v_mul_f32_e32 v0, v130, v0
	v_exp_f32_e32 v0, v0
	v_mov_b32_e32 v136, v77
	v_mul_f32_e32 v92, v92, v0
	v_pk_mul_f32 v[18:19], v[18:19], v[0:1] op_sel_hi:[1,0]
	v_pk_mul_f32 v[16:17], v[16:17], v[0:1] op_sel_hi:[1,0]
	v_pk_mul_f32 v[14:15], v[14:15], v[0:1] op_sel_hi:[1,0]
	v_pk_mul_f32 v[12:13], v[12:13], v[0:1] op_sel_hi:[1,0]
	v_pk_mul_f32 v[10:11], v[10:11], v[0:1] op_sel_hi:[1,0]
	v_pk_mul_f32 v[8:9], v[8:9], v[0:1] op_sel_hi:[1,0]
	v_pk_mul_f32 v[6:7], v[6:7], v[0:1] op_sel_hi:[1,0]
	v_pk_mul_f32 v[4:5], v[4:5], v[0:1] op_sel_hi:[1,0]
	s_branch .LBB0_431

; __device__ __forceinline__ float qmax(float x) { float a = x, b = x; swap16(a, b); a = fmaxf(a, b); b = a; swap32(a, b); return fmaxf(a, b); }
; __device__ __forceinline__ void softmax_pv(float& m, float& l, f32x4 (&o)[4], f32x4 s0, f32x4 s1, const bf16x8 (&vf)[4], float kL2e) {
;     float mx = fmaxf(fmaxf(fmaxf(s0[0], s0[1]), fmaxf(s0[2], s0[3])), fmaxf(fmaxf(s1[0], s1[1]), fmaxf(s1[2], s1[3])));
;     mx = qmax(mx);
;     const float mn = fmaxf(m, mx);
;     if (__builtin_amdgcn_ballot_w64(mn > m) != 0ull) {
;         const float alpha = __builtin_amdgcn_exp2f((m - mn) * kL2e);
;         l *= alpha;
; #pragma unroll
;         for (int dt = 0; dt < 4; ++dt) o[dt] = o[dt] * alpha;
;         m = mn;
.LBB0_446:
	v_max_f32_e32 v0, v0, v3
	v_max_f32_e32 v109, v149, v151
	v_max_f32_e32 v110, v150, v152
	v_max3_f32 v110, v2, v129, v110
	v_max3_f32 v0, v0, v109, v110
	v_mov_b32_e32 v109, v0
	s_nop 1
	v_permlane16_swap_b32 v109, v0
	s_nop 1
	s_nop 0
	v_max_f32_e32 v0, v109, v0
	v_mov_b32_e32 v109, v0
	s_nop 1
	v_permlane32_swap_b32 v109, v0
	s_nop 1
	s_nop 0
	v_max3_f32 v109, v137, v109, v0
	v_cmp_gt_f32_e32 vcc, v109, v137
	s_cbranch_vccz .LBB0_448
	v_sub_f32_e32 v0, v137, v109
	v_mul_f32_e32 v0, v130, v0
	v_exp_f32_e32 v0, v0
	v_mov_b32_e32 v137, v109
	v_mul_f32_e32 v139, v139, v0
	v_pk_mul_f32 v[34:35], v[34:35], v[0:1] op_sel_hi:[1,0]
	v_pk_mul_f32 v[32:33], v[32:33], v[0:1] op_sel_hi:[1,0]
	v_pk_mul_f32 v[30:31], v[30:31], v[0:1] op_sel_hi:[1,0]
	v_pk_mul_f32 v[28:29], v[28:29], v[0:1] op_sel_hi:[1,0]
	v_pk_mul_f32 v[26:27], v[26:27], v[0:1] op_sel_hi:[1,0]
	v_pk_mul_f32 v[24:25], v[24:25], v[0:1] op_sel_hi:[1,0]
	v_pk_mul_f32 v[22:23], v[22:23], v[0:1] op_sel_hi:[1,0]
	v_pk_mul_f32 v[20:21], v[20:21], v[0:1] op_sel_hi:[1,0]
	s_branch .LBB0_449

; __device__ __forceinline__ float qmax(float x) { float a = x, b = x; swap16(a, b); a = fmaxf(a, b); b = a; swap32(a, b); return fmaxf(a, b); }
; __device__ __forceinline__ void softmax_pv(float& m, float& l, f32x4 (&o)[4], f32x4 s0, f32x4 s1, const bf16x8 (&vf)[4], float kL2e) {
;     float mx = fmaxf(fmaxf(fmaxf(s0[0], s0[1]), fmaxf(s0[2], s0[3])), fmaxf(fmaxf(s1[0], s1[1]), fmaxf(s1[2], s1[3])));
;     mx = qmax(mx);
;     const float mn = fmaxf(m, mx);
;     if (__builtin_amdgcn_ballot_w64(mn > m) != 0ull) {
;         const float alpha = __builtin_amdgcn_exp2f((m - mn) * kL2e);
;         l *= alpha;
; #pragma unroll
;         for (int dt = 0; dt < 4; ++dt) o[dt] = o[dt] * alpha;
;         m = mn;
.LBB0_454:
	v_max_f32_e32 v0, v0, v104
	v_max_f32_e32 v93, v106, v108
	v_max_f32_e32 v94, v107, v109
	v_max3_f32 v94, v3, v105, v94
	v_max3_f32 v0, v0, v93, v94
	v_mov_b32_e32 v93, v0
	s_nop 1
	v_permlane16_swap_b32 v0, v93
	s_nop 1
	s_nop 0
	v_max_f32_e32 v0, v0, v93
	v_mov_b32_e32 v93, v0
	s_nop 1
	v_permlane32_swap_b32 v0, v93
	s_nop 1
	s_nop 0
	v_max3_f32 v93, v137, v0, v93
	v_cmp_gt_f32_e32 vcc, v93, v137
	s_cbranch_vccz .LBB0_456
	v_sub_f32_e32 v0, v137, v93
	v_mul_f32_e32 v0, v130, v0
	v_exp_f32_e32 v0, v0
	v_mov_b32_e32 v137, v93
	v_mul_f32_e32 v139, v2, v0
	v_pk_mul_f32 v[34:35], v[34:35], v[0:1] op_sel_hi:[1,0]
	v_pk_mul_f32 v[32:33], v[32:33], v[0:1] op_sel_hi:[1,0]
	v_pk_mul_f32 v[30:31], v[30:31], v[0:1] op_sel_hi:[1,0]
	v_pk_mul_f32 v[28:29], v[28:29], v[0:1] op_sel_hi:[1,0]
	v_pk_mul_f32 v[26:27], v[26:27], v[0:1] op_sel_hi:[1,0]
	v_pk_mul_f32 v[24:25], v[24:25], v[0:1] op_sel_hi:[1,0]
	v_pk_mul_f32 v[22:23], v[22:23], v[0:1] op_sel_hi:[1,0]
	v_pk_mul_f32 v[20:21], v[20:21], v[0:1] op_sel_hi:[1,0]
	s_branch .LBB0_457

; __device__ __forceinline__ float qmax(float x) { float a = x, b = x; swap16(a, b); a = fmaxf(a, b); b = a; swap32(a, b); return fmaxf(a, b); }
; __device__ __forceinline__ void softmax_pv(float& m, float& l, f32x4 (&o)[4], f32x4 s0, f32x4 s1, const bf16x8 (&vf)[4], float kL2e) {
;     float mx = fmaxf(fmaxf(fmaxf(s0[0], s0[1]), fmaxf(s0[2], s0[3])), fmaxf(fmaxf(s1[0], s1[1]), fmaxf(s1[2], s1[3])));
;     mx = qmax(mx);
;     const float mn = fmaxf(m, mx);
;     if (__builtin_amdgcn_ballot_w64(mn > m) != 0ull) {
;         const float alpha = __builtin_amdgcn_exp2f((m - mn) * kL2e);
;         l *= alpha;
; #pragma unroll
;         for (int dt = 0; dt < 4; ++dt) o[dt] = o[dt] * alpha;
;         m = mn;
.LBB0_466:
	v_max_f32_e32 v0, v0, v152
	v_max_f32_e32 v117, v156, v177
	v_max_f32_e32 v118, v157, v178
	v_max3_f32 v118, v151, v153, v118
	v_max3_f32 v0, v0, v117, v118
	v_mov_b32_e32 v117, v0
	s_nop 1
	v_permlane16_swap_b32 v0, v117
	s_nop 1
	s_nop 0
	v_max_f32_e32 v0, v0, v117
	v_mov_b32_e32 v117, v0
	s_nop 1
	v_permlane32_swap_b32 v0, v117
	s_nop 1
	s_nop 0
	v_max3_f32 v117, v136, v0, v117
	v_cmp_gt_f32_e32 vcc, v117, v136
	s_cbranch_vccz .LBB0_468
	v_sub_f32_e32 v0, v136, v117
	v_mul_f32_e32 v0, v130, v0
	v_exp_f32_e32 v0, v0
	v_mov_b32_e32 v136, v117
	v_mul_f32_e32 v138, v138, v0
	v_pk_mul_f32 v[18:19], v[18:19], v[0:1] op_sel_hi:[1,0]
	v_pk_mul_f32 v[16:17], v[16:17], v[0:1] op_sel_hi:[1,0]
	v_pk_mul_f32 v[14:15], v[14:15], v[0:1] op_sel_hi:[1,0]
	v_pk_mul_f32 v[12:13], v[12:13], v[0:1] op_sel_hi:[1,0]
	v_pk_mul_f32 v[10:11], v[10:11], v[0:1] op_sel_hi:[1,0]
	v_pk_mul_f32 v[8:9], v[8:9], v[0:1] op_sel_hi:[1,0]
	v_pk_mul_f32 v[6:7], v[6:7], v[0:1] op_sel_hi:[1,0]
	v_pk_mul_f32 v[4:5], v[4:5], v[0:1] op_sel_hi:[1,0]
	s_branch .LBB0_469

; __device__ __forceinline__ float qmax(float x) { float a = x, b = x; swap16(a, b); a = fmaxf(a, b); b = a; swap32(a, b); return fmaxf(a, b); }
; __device__ __forceinline__ void softmax_pv(float& m, float& l, f32x4 (&o)[4], f32x4 s0, f32x4 s1, const bf16x8 (&vf)[4], float kL2e) {
;     float mx = fmaxf(fmaxf(fmaxf(s0[0], s0[1]), fmaxf(s0[2], s0[3])), fmaxf(fmaxf(s1[0], s1[1]), fmaxf(s1[2], s1[3])));
;     mx = qmax(mx);
;     const float mn = fmaxf(m, mx);
;     if (__builtin_amdgcn_ballot_w64(mn > m) != 0ull) {
;         const float alpha = __builtin_amdgcn_exp2f((m - mn) * kL2e);
;         l *= alpha;
; #pragma unroll
;         for (int dt = 0; dt < 4; ++dt) o[dt] = o[dt] * alpha;
;         m = mn;
;     }
;     const float mb = m * kL2e;
;     f32x4 p0, p1;
; #pragma unroll
;     for (int e = 0; e < 4; ++e) { p0[e] = __builtin_amdgcn_exp2f(s0[e] * kL2e - mb); p1[e] = __builtin_amdgcn_exp2f(s1[e] * kL2e - mb); }
;     l += ((p0[0] + p0[1]) + (p0[2] + p0[3])) + ((p1[0] + p1[1]) + (p1[2] + p1[3]));
.LBB0_473:
	s_nop 3
	v_pk_add_f32 v[118:119], v[150:151], v[154:155]
	v_pk_add_f32 v[120:121], v[152:153], v[156:157]
	v_max_f32_e32 v117, v178, v178
	v_pk_add_f32 v[118:119], v[118:119], v[120:121]
	v_max_f32_e32 v0, v0, v0
	v_pk_add_f32 v[118:119], v[118:119], v[118:119] op_sel:[0,1] op_sel_hi:[1,0]
	v_max_f32_e32 v0, v0, v117
	v_pk_add_f32 v[150:151], v[138:139], v[118:119]
	v_max_f32_e32 v117, v180, v182
	v_max_f32_e32 v118, v181, v183
	v_max3_f32 v118, v177, v179, v118
	v_max3_f32 v0, v0, v117, v118
	v_mov_b32_e32 v117, v0
	s_nop 1
	v_permlane16_swap_b32 v117, v0
	s_nop 1
	s_nop 0
	v_max_f32_e32 v0, v117, v0
	v_mov_b32_e32 v117, v0
	s_nop 1
	v_permlane32_swap_b32 v117, v0
	s_nop 1
	s_nop 0
	v_max3_f32 v117, v137, v117, v0
	v_cmp_gt_f32_e32 vcc, v117, v137
	s_cbranch_vccz .LBB0_475
	v_sub_f32_e32 v0, v137, v117
	v_mul_f32_e32 v0, v130, v0
	v_exp_f32_e32 v0, v0
	v_mov_b32_e32 v137, v117
	v_mul_f32_e32 v139, v139, v0
	v_pk_mul_f32 v[34:35], v[34:35], v[0:1] op_sel_hi:[1,0]
	v_pk_mul_f32 v[32:33], v[32:33], v[0:1] op_sel_hi:[1,0]
	v_pk_mul_f32 v[30:31], v[30:31], v[0:1] op_sel_hi:[1,0]
	v_pk_mul_f32 v[28:29], v[28:29], v[0:1] op_sel_hi:[1,0]
	v_pk_mul_f32 v[26:27], v[26:27], v[0:1] op_sel_hi:[1,0]
	v_pk_mul_f32 v[24:25], v[24:25], v[0:1] op_sel_hi:[1,0]
	v_pk_mul_f32 v[22:23], v[22:23], v[0:1] op_sel_hi:[1,0]
	v_pk_mul_f32 v[20:21], v[20:21], v[0:1] op_sel_hi:[1,0]
	s_branch .LBB0_476

; __device__ __forceinline__ float qmax(float x) { float a = x, b = x; swap16(a, b); a = fmaxf(a, b); b = a; swap32(a, b); return fmaxf(a, b); }
; __device__ __forceinline__ void softmax_pv(float& m, float& l, f32x4 (&o)[4], f32x4 s0, f32x4 s1, const bf16x8 (&vf)[4], float kL2e) {
;     float mx = fmaxf(fmaxf(fmaxf(s0[0], s0[1]), fmaxf(s0[2], s0[3])), fmaxf(fmaxf(s1[0], s1[1]), fmaxf(s1[2], s1[3])));
;     mx = qmax(mx);
;     const float mn = fmaxf(m, mx);
;     if (__builtin_amdgcn_ballot_w64(mn > m) != 0ull) {
;         const float alpha = __builtin_amdgcn_exp2f((m - mn) * kL2e);
;         l *= alpha;
; #pragma unroll
;         for (int dt = 0; dt < 4; ++dt) o[dt] = o[dt] * alpha;
;         m = mn;
.LBB0_481:
	v_max_f32_e32 v0, v0, v170
	v_max_f32_e32 v117, v172, v174
	v_max_f32_e32 v118, v173, v175
	v_max3_f32 v118, v167, v171, v118
	v_max3_f32 v0, v0, v117, v118
	v_mov_b32_e32 v117, v0
	s_nop 1
	v_permlane16_swap_b32 v0, v117
	s_nop 1
	s_nop 0
	v_max_f32_e32 v0, v0, v117
	v_mov_b32_e32 v117, v0
	s_nop 1
	v_permlane32_swap_b32 v0, v117
	s_nop 1
	s_nop 0
	v_max3_f32 v117, v136, v0, v117
	v_cmp_gt_f32_e32 vcc, v117, v136
	s_cbranch_vccz .LBB0_483
	v_sub_f32_e32 v0, v136, v117
	v_mul_f32_e32 v0, v130, v0
	v_exp_f32_e32 v0, v0
	v_mov_b32_e32 v136, v117
	v_mul_f32_e32 v150, v150, v0
	v_pk_mul_f32 v[18:19], v[18:19], v[0:1] op_sel_hi:[1,0]
	v_pk_mul_f32 v[16:17], v[16:17], v[0:1] op_sel_hi:[1,0]
	v_pk_mul_f32 v[14:15], v[14:15], v[0:1] op_sel_hi:[1,0]
	v_pk_mul_f32 v[12:13], v[12:13], v[0:1] op_sel_hi:[1,0]
	v_pk_mul_f32 v[10:11], v[10:11], v[0:1] op_sel_hi:[1,0]
	v_pk_mul_f32 v[8:9], v[8:9], v[0:1] op_sel_hi:[1,0]
	v_pk_mul_f32 v[6:7], v[6:7], v[0:1] op_sel_hi:[1,0]
	v_pk_mul_f32 v[4:5], v[4:5], v[0:1] op_sel_hi:[1,0]
	s_branch .LBB0_484

; __device__ __forceinline__ float qmax(float x) { float a = x, b = x; swap16(a, b); a = fmaxf(a, b); b = a; swap32(a, b); return fmaxf(a, b); }
; __device__ __forceinline__ void softmax_pv(float& m, float& l, f32x4 (&o)[4], f32x4 s0, f32x4 s1, const bf16x8 (&vf)[4], float kL2e) {
;     float mx = fmaxf(fmaxf(fmaxf(s0[0], s0[1]), fmaxf(s0[2], s0[3])), fmaxf(fmaxf(s1[0], s1[1]), fmaxf(s1[2], s1[3])));
;     mx = qmax(mx);
;     const float mn = fmaxf(m, mx);
;     if (__builtin_amdgcn_ballot_w64(mn > m) != 0ull) {
;         const float alpha = __builtin_amdgcn_exp2f((m - mn) * kL2e);
;         l *= alpha;
; #pragma unroll
;         for (int dt = 0; dt < 4; ++dt) o[dt] = o[dt] * alpha;
;         m = mn;
;     }
;     const float mb = m * kL2e;
;     f32x4 p0, p1;
; #pragma unroll
;     for (int e = 0; e < 4; ++e) { p0[e] = __builtin_amdgcn_exp2f(s0[e] * kL2e - mb); p1[e] = __builtin_amdgcn_exp2f(s1[e] * kL2e - mb); }
;     l += ((p0[0] + p0[1]) + (p0[2] + p0[3])) + ((p1[0] + p1[1]) + (p1[2] + p1[3]));
.LBB0_488:
	s_nop 3
	v_pk_add_f32 v[102:103], v[120:121], v[124:125]
	v_pk_add_f32 v[104:105], v[122:123], v[126:127]
	v_max_f32_e32 v101, v109, v109
	v_pk_add_f32 v[102:103], v[102:103], v[104:105]
	v_max_f32_e32 v0, v0, v0
	v_pk_add_f32 v[102:103], v[102:103], v[102:103] op_sel:[0,1] op_sel_hi:[1,0]
	v_max_f32_e32 v0, v0, v101
	v_pk_add_f32 v[138:139], v[150:151], v[102:103]
	v_max_f32_e32 v101, v111, v113
	v_max_f32_e32 v102, v112, v114
	v_max3_f32 v102, v108, v110, v102
	v_max3_f32 v0, v0, v101, v102
	v_mov_b32_e32 v101, v0
	s_nop 1
	v_permlane16_swap_b32 v101, v0
	s_nop 1
	s_nop 0
	v_max_f32_e32 v0, v101, v0
	v_mov_b32_e32 v101, v0
	s_nop 1
	v_permlane32_swap_b32 v101, v0
	s_nop 1
	s_nop 0
	v_max3_f32 v101, v137, v101, v0
	v_cmp_gt_f32_e32 vcc, v101, v137
	s_cbranch_vccz .LBB0_490
	v_sub_f32_e32 v0, v137, v101
	v_mul_f32_e32 v0, v130, v0
	v_exp_f32_e32 v0, v0
	v_mov_b32_e32 v137, v101
	v_mul_f32_e32 v151, v151, v0
	v_pk_mul_f32 v[34:35], v[34:35], v[0:1] op_sel_hi:[1,0]
	v_pk_mul_f32 v[32:33], v[32:33], v[0:1] op_sel_hi:[1,0]
	v_pk_mul_f32 v[30:31], v[30:31], v[0:1] op_sel_hi:[1,0]
	v_pk_mul_f32 v[28:29], v[28:29], v[0:1] op_sel_hi:[1,0]
	v_pk_mul_f32 v[26:27], v[26:27], v[0:1] op_sel_hi:[1,0]
	v_pk_mul_f32 v[24:25], v[24:25], v[0:1] op_sel_hi:[1,0]
	v_pk_mul_f32 v[22:23], v[22:23], v[0:1] op_sel_hi:[1,0]
	v_pk_mul_f32 v[20:21], v[20:21], v[0:1] op_sel_hi:[1,0]
	s_branch .LBB0_491

; __device__ __forceinline__ float qmax(float x) { float a = x, b = x; swap16(a, b); a = fmaxf(a, b); b = a; swap32(a, b); return fmaxf(a, b); }
; __device__ __forceinline__ void softmax_pv(float& m, float& l, f32x4 (&o)[4], f32x4 s0, f32x4 s1, const bf16x8 (&vf)[4], float kL2e) {
;     float mx = fmaxf(fmaxf(fmaxf(s0[0], s0[1]), fmaxf(s0[2], s0[3])), fmaxf(fmaxf(s1[0], s1[1]), fmaxf(s1[2], s1[3])));
;     mx = qmax(mx);
;     const float mn = fmaxf(m, mx);
;     if (__builtin_amdgcn_ballot_w64(mn > m) != 0ull) {
;         const float alpha = __builtin_amdgcn_exp2f((m - mn) * kL2e);
;         l *= alpha;
; #pragma unroll
;         for (int dt = 0; dt < 4; ++dt) o[dt] = o[dt] * alpha;
;         m = mn;
.LBB0_501:
	v_max_f32_e32 v0, v0, v111
	v_max_f32_e32 v2, v113, v115
	v_max_f32_e32 v85, v114, v116
	v_max3_f32 v85, v3, v112, v85
	v_max3_f32 v0, v0, v2, v85
	v_mov_b32_e32 v2, v0
	s_nop 1
	v_permlane16_swap_b32 v2, v0
	s_nop 1
	s_nop 0
	v_max_f32_e32 v0, v2, v0
	v_mov_b32_e32 v2, v0
	s_nop 1
	v_permlane32_swap_b32 v2, v0
	s_nop 1
	s_nop 0
	v_max3_f32 v85, v136, v2, v0
	v_cmp_gt_f32_e32 vcc, v85, v136
	s_cbranch_vccz .LBB0_504
	v_sub_f32_e32 v0, v136, v85
	v_mul_f32_e32 v0, v130, v0
	v_exp_f32_e32 v0, v0
	v_mov_b32_e32 v136, v85
	v_mul_f32_e32 v138, v138, v0
	v_pk_mul_f32 v[18:19], v[18:19], v[0:1] op_sel_hi:[1,0]
	v_pk_mul_f32 v[16:17], v[16:17], v[0:1] op_sel_hi:[1,0]
	v_pk_mul_f32 v[14:15], v[14:15], v[0:1] op_sel_hi:[1,0]
	v_pk_mul_f32 v[12:13], v[12:13], v[0:1] op_sel_hi:[1,0]
	v_pk_mul_f32 v[10:11], v[10:11], v[0:1] op_sel_hi:[1,0]
	v_pk_mul_f32 v[8:9], v[8:9], v[0:1] op_sel_hi:[1,0]
	v_pk_mul_f32 v[6:7], v[6:7], v[0:1] op_sel_hi:[1,0]
	v_pk_mul_f32 v[4:5], v[4:5], v[0:1] op_sel_hi:[1,0]
	s_branch .LBB0_505

; __device__ __forceinline__ float qmax(float x) { float a = x, b = x; swap16(a, b); a = fmaxf(a, b); b = a; swap32(a, b); return fmaxf(a, b); }
; __device__ __forceinline__ void softmax_pv(float& m, float& l, f32x4 (&o)[4], f32x4 s0, f32x4 s1, const bf16x8 (&vf)[4], float kL2e) {
;     float mx = fmaxf(fmaxf(fmaxf(s0[0], s0[1]), fmaxf(s0[2], s0[3])), fmaxf(fmaxf(s1[0], s1[1]), fmaxf(s1[2], s1[3])));
;     mx = qmax(mx);
;     const float mn = fmaxf(m, mx);
;     if (__builtin_amdgcn_ballot_w64(mn > m) != 0ull) {
;         const float alpha = __builtin_amdgcn_exp2f((m - mn) * kL2e);
;         l *= alpha;
; #pragma unroll
;         for (int dt = 0; dt < 4; ++dt) o[dt] = o[dt] * alpha;
;         m = mn;
.LBB0_512:
	v_max_f32_e32 v153, v162, v150
	v_max_f32_e32 v158, v151, v152
	v_max_f32_e32 v159, v156, v157
	v_max3_f32 v159, v154, v155, v159
	v_max3_f32 v153, v153, v158, v159
	v_mov_b32_e32 v158, v153
	s_nop 1
	v_permlane16_swap_b32 v158, v153
	s_nop 1
	s_nop 0
	v_max_f32_e32 v153, v158, v153
	v_mov_b32_e32 v158, v153
	s_nop 1
	v_permlane32_swap_b32 v158, v153
	s_nop 1
	s_nop 0
	v_max3_f32 v163, v202, v158, v153
	v_cmp_gt_f32_e32 vcc, v163, v202
	s_cbranch_vccz .LBB0_620
	v_sub_f32_e32 v153, v202, v163
	v_mul_f32_e32 v153, v20, v153
	v_exp_f32_e32 v158, v153
	s_nop 0
	v_mul_f32_e32 v18, v18, v158
	v_pk_mul_f32 v[16:17], v[16:17], v[158:159] op_sel_hi:[1,0]
	v_pk_mul_f32 v[14:15], v[14:15], v[158:159] op_sel_hi:[1,0]
	v_pk_mul_f32 v[12:13], v[12:13], v[158:159] op_sel_hi:[1,0]
	v_pk_mul_f32 v[10:11], v[10:11], v[158:159] op_sel_hi:[1,0]
	v_pk_mul_f32 v[8:9], v[8:9], v[158:159] op_sel_hi:[1,0]
	v_pk_mul_f32 v[6:7], v[6:7], v[158:159] op_sel_hi:[1,0]
	v_pk_mul_f32 v[4:5], v[4:5], v[158:159] op_sel_hi:[1,0]
	v_pk_mul_f32 v[2:3], v[2:3], v[158:159] op_sel_hi:[1,0]

; __device__ __forceinline__ float qmax(float x) { float a = x, b = x; swap16(a, b); a = fmaxf(a, b); b = a; swap32(a, b); return fmaxf(a, b); }
; __device__ __forceinline__ void softmax_pv(float& m, float& l, f32x4 (&o)[4], f32x4 s0, f32x4 s1, const bf16x8 (&vf)[4], float kL2e) {
;     float mx = fmaxf(fmaxf(fmaxf(s0[0], s0[1]), fmaxf(s0[2], s0[3])), fmaxf(fmaxf(s1[0], s1[1]), fmaxf(s1[2], s1[3])));
;     mx = qmax(mx);
;     const float mn = fmaxf(m, mx);
;     if (__builtin_amdgcn_ballot_w64(mn > m) != 0ull) {
;         const float alpha = __builtin_amdgcn_exp2f((m - mn) * kL2e);
;         l *= alpha;
; #pragma unroll
;         for (int dt = 0; dt < 4; ++dt) o[dt] = o[dt] * alpha;
;         m = mn;
.LBB0_516:
	v_add_u32_e32 v218, s43, v198
	v_add_u32_e32 v219, s43, v197
	v_add_u32_e32 v220, s43, v196
	v_add_u32_e32 v221, s43, v195
	v_add_u32_e32 v222, s43, v194
	v_add_u32_e32 v223, s43, v193
	v_add_u32_e32 v224, s43, v192
	v_add_u32_e32 v225, s43, v191
	s_add_i32 s48, s49, 1
	s_min_i32 s22, s48, s31
	s_add_i32 s22, s22, s1
	s_lshl_b32 s22, s22, 6
	s_add_i32 s22, s22, s30
	s_waitcnt vmcnt(3)
	v_mad_i64_i32 v[134:135], s[24:25], s22, v242, v[182:183]
	s_movk_i32 s24, 0x5000
	s_ashr_i32 s23, s22, 31
	global_load_dwordx4 v[150:153], v[134:135], off
	global_load_dwordx4 v[154:157], v[134:135], off offset:64
	v_add_co_u32_e32 v134, vcc, s24, v134
	s_waitcnt vmcnt(2)
	v_lshl_add_u64 v[142:143], s[22:23], 1, v[184:185]
	v_addc_co_u32_e32 v135, vcc, 0, v135, vcc
	v_add_co_u32_e32 v138, vcc, s45, v142
	global_load_dwordx4 v[162:165], v[134:135], off offset:2048
	global_load_dwordx4 v[158:161], v[134:135], off offset:2112
	v_addc_co_u32_e32 v139, vcc, 0, v143, vcc
	v_add_co_u32_e32 v144, vcc, 0x121000, v142
	global_load_dwordx4 v[134:137], v[142:143], off
	s_nop 0
	global_load_dwordx4 v[138:141], v[138:139], off offset:2048
	v_addc_co_u32_e32 v145, vcc, 0, v143, vcc
	v_add_co_u32_e32 v142, vcc, 0x1b1000, v142
	s_cmp_lt_u32 s49, 8
	s_nop 0
	v_addc_co_u32_e32 v143, vcc, 0, v143, vcc
	global_load_dwordx4 v[146:149], v[144:145], off
	s_nop 0
	global_load_dwordx4 v[142:145], v[142:143], off offset:2048
	s_cselect_b64 s[22:23], -1, 0
	s_cmp_gt_u32 s49, 7
	s_cbranch_scc1 .LBB0_537
	s_waitcnt vmcnt(8)
	v_mfma_f32_16x16x32_bf16 v[166:169], v[102:105], v[82:85], 0
	v_mfma_f32_16x16x32_bf16 v[170:173], v[106:109], v[78:81], v[166:169]
	v_mfma_f32_16x16x32_bf16 v[166:169], v[110:113], v[82:85], 0
	v_mfma_f32_16x16x32_bf16 v[166:169], v[114:117], v[78:81], v[166:169]
	ds_read_b32 v210, v218 offset:868
	ds_read_b32 v211, v219 offset:868
	ds_read_b32 v212, v220 offset:868
	ds_read_b32 v213, v221 offset:868
	ds_read_b32 v214, v222 offset:868
	ds_read_b32 v215, v223 offset:868
	ds_read_b32 v216, v224 offset:868
	ds_read_b32 v217, v225 offset:868
	s_waitcnt lgkmcnt(0)
	v_add_f32_e32 v210, v170, v210
	v_add_f32_e32 v211, v166, v211
	v_add_f32_e32 v212, v171, v212
	v_add_f32_e32 v213, v167, v213
	v_add_f32_e32 v214, v172, v214
	v_add_f32_e32 v215, v168, v215
	v_add_f32_e32 v216, v173, v216
	v_add_f32_e32 v217, v169, v217
	v_cndmask_b32_e64 v186, v19, v210, s[6:7]
	v_cndmask_b32_e64 v170, v19, v211, s[8:9]
	v_cndmask_b32_e64 v166, v19, v212, s[10:11]
	v_cndmask_b32_e64 v171, v19, v213, s[14:15]
	v_cndmask_b32_e64 v167, v19, v214, s[16:17]
	v_cndmask_b32_e64 v172, v19, v215, s[18:19]
	v_cndmask_b32_e64 v168, v19, v216, s[20:21]
	v_cndmask_b32_e64 v173, v19, v217, s[2:3]
	v_max_f32_e32 v169, v186, v166
	v_max_f32_e32 v187, v167, v168
	v_max_f32_e32 v203, v172, v173
	v_max3_f32 v203, v170, v171, v203
	v_max3_f32 v169, v169, v187, v203
	v_mov_b32_e32 v187, v169
	s_nop 1
	v_permlane16_swap_b32 v169, v187
	s_nop 1
	s_nop 0
	v_max_f32_e32 v169, v169, v187
	v_mov_b32_e32 v187, v169
	s_nop 1
	v_permlane32_swap_b32 v169, v187
	s_nop 1
	s_nop 0
	v_max3_f32 v187, v199, v169, v187
	v_cmp_gt_f32_e32 vcc, v187, v199
	s_cbranch_vccz .LBB0_535
	v_sub_f32_e32 v169, v199, v187
	v_mul_f32_e32 v169, v20, v169
	v_exp_f32_e32 v204, v169
	s_nop 0
	v_mul_f32_e32 v190, v190, v204
	v_pk_mul_f32 v[100:101], v[100:101], v[204:205] op_sel_hi:[1,0]
	v_pk_mul_f32 v[98:99], v[98:99], v[204:205] op_sel_hi:[1,0]
	v_pk_mul_f32 v[96:97], v[96:97], v[204:205] op_sel_hi:[1,0]
	v_pk_mul_f32 v[94:95], v[94:95], v[204:205] op_sel_hi:[1,0]
	v_pk_mul_f32 v[92:93], v[92:93], v[204:205] op_sel_hi:[1,0]
	v_pk_mul_f32 v[90:91], v[90:91], v[204:205] op_sel_hi:[1,0]
	v_pk_mul_f32 v[88:89], v[88:89], v[204:205] op_sel_hi:[1,0]
	v_pk_mul_f32 v[86:87], v[86:87], v[204:205] op_sel_hi:[1,0]
	s_branch .LBB0_536

; __device__ __forceinline__ float qmax(float x) { float a = x, b = x; swap16(a, b); a = fmaxf(a, b); b = a; swap32(a, b); return fmaxf(a, b); }
; __device__ __forceinline__ void softmax_pv(float& m, float& l, f32x4 (&o)[4], f32x4 s0, f32x4 s1, const bf16x8 (&vf)[4], float kL2e) {
;     float mx = fmaxf(fmaxf(fmaxf(s0[0], s0[1]), fmaxf(s0[2], s0[3])), fmaxf(fmaxf(s1[0], s1[1]), fmaxf(s1[2], s1[3])));
;     mx = qmax(mx);
;     const float mn = fmaxf(m, mx);
;     if (__builtin_amdgcn_ballot_w64(mn > m) != 0ull) {
;         const float alpha = __builtin_amdgcn_exp2f((m - mn) * kL2e);
;         l *= alpha;
; #pragma unroll
;         for (int dt = 0; dt < 4; ++dt) o[dt] = o[dt] * alpha;
;         m = mn;
.LBB0_537:
	s_add_i32 s50, s1, s49
	s_cmp_ge_u32 s50, s27
	s_cselect_b64 s[24:25], -1, 0
	s_cmp_lt_u32 s50, s34
	s_cselect_b64 s[56:57], -1, 0
	s_and_b64 s[24:25], s[24:25], s[56:57]
	s_andn2_b64 vcc, exec, s[24:25]
	s_cbranch_vccnz .LBB0_558
	s_waitcnt vmcnt(8)
	v_mfma_f32_16x16x32_bf16 v[166:169], v[102:105], v[74:77], 0
	v_mfma_f32_16x16x32_bf16 v[170:173], v[106:109], v[70:73], v[166:169]
	v_mfma_f32_16x16x32_bf16 v[166:169], v[110:113], v[74:77], 0
	v_mfma_f32_16x16x32_bf16 v[166:169], v[114:117], v[70:73], v[166:169]
	ds_read_b32 v210, v218 offset:744
	ds_read_b32 v211, v219 offset:744
	ds_read_b32 v212, v220 offset:744
	ds_read_b32 v213, v221 offset:744
	ds_read_b32 v214, v222 offset:744
	ds_read_b32 v215, v223 offset:744
	ds_read_b32 v216, v224 offset:744
	ds_read_b32 v217, v225 offset:744
	s_waitcnt lgkmcnt(0)
	v_add_f32_e32 v210, v170, v210
	v_add_f32_e32 v211, v166, v211
	v_add_f32_e32 v212, v171, v212
	v_add_f32_e32 v213, v167, v213
	v_add_f32_e32 v214, v172, v214
	v_add_f32_e32 v215, v168, v215
	v_add_f32_e32 v216, v173, v216
	v_add_f32_e32 v217, v169, v217
	v_cndmask_b32_e64 v186, v19, v210, s[6:7]
	v_cndmask_b32_e64 v170, v19, v211, s[8:9]
	v_cndmask_b32_e64 v166, v19, v212, s[10:11]
	v_cndmask_b32_e64 v171, v19, v213, s[14:15]
	v_cndmask_b32_e64 v167, v19, v214, s[16:17]
	v_cndmask_b32_e64 v172, v19, v215, s[18:19]
	v_cndmask_b32_e64 v168, v19, v216, s[20:21]
	v_cndmask_b32_e64 v173, v19, v217, s[2:3]
	v_max_f32_e32 v169, v186, v166
	v_max_f32_e32 v187, v167, v168
	v_max_f32_e32 v203, v172, v173
	v_max3_f32 v203, v170, v171, v203
	v_max3_f32 v169, v169, v187, v203
	v_mov_b32_e32 v187, v169
	s_nop 1
	v_permlane16_swap_b32 v169, v187
	s_nop 1
	s_nop 0
	v_max_f32_e32 v169, v169, v187
	v_mov_b32_e32 v187, v169
	s_nop 1
	v_permlane32_swap_b32 v169, v187
	s_nop 1
	s_nop 0
	v_max3_f32 v187, v200, v169, v187
	v_cmp_gt_f32_e32 vcc, v187, v200
	s_cbranch_vccz .LBB0_556
	v_sub_f32_e32 v169, v200, v187
	v_mul_f32_e32 v169, v20, v169
	v_exp_f32_e32 v200, v169
	s_nop 0
	v_mul_f32_e32 v189, v189, v200
	v_pk_mul_f32 v[68:69], v[68:69], v[200:201] op_sel_hi:[1,0]
	v_pk_mul_f32 v[66:67], v[66:67], v[200:201] op_sel_hi:[1,0]
	v_pk_mul_f32 v[56:57], v[56:57], v[200:201] op_sel_hi:[1,0]
	v_pk_mul_f32 v[54:55], v[54:55], v[200:201] op_sel_hi:[1,0]
	v_pk_mul_f32 v[48:49], v[48:49], v[200:201] op_sel_hi:[1,0]
	v_pk_mul_f32 v[46:47], v[46:47], v[200:201] op_sel_hi:[1,0]
	v_pk_mul_f32 v[40:41], v[40:41], v[200:201] op_sel_hi:[1,0]
	v_pk_mul_f32 v[38:39], v[38:39], v[200:201] op_sel_hi:[1,0]
	s_branch .LBB0_557

; __device__ __forceinline__ float qmax(float x) { float a = x, b = x; swap16(a, b); a = fmaxf(a, b); b = a; swap32(a, b); return fmaxf(a, b); }
; __device__ __forceinline__ void softmax_pv(float& m, float& l, f32x4 (&o)[4], f32x4 s0, f32x4 s1, const bf16x8 (&vf)[4], float kL2e) {
;     float mx = fmaxf(fmaxf(fmaxf(s0[0], s0[1]), fmaxf(s0[2], s0[3])), fmaxf(fmaxf(s1[0], s1[1]), fmaxf(s1[2], s1[3])));
;     mx = qmax(mx);
;     const float mn = fmaxf(m, mx);
;     if (__builtin_amdgcn_ballot_w64(mn > m) != 0ull) {
;         const float alpha = __builtin_amdgcn_exp2f((m - mn) * kL2e);
;         l *= alpha;
; #pragma unroll
;         for (int dt = 0; dt < 4; ++dt) o[dt] = o[dt] * alpha;
;         m = mn;
.LBB0_558:
	s_cmp_ge_u32 s50, s28
	s_cselect_b64 s[24:25], -1, 0
	s_cmp_lt_u32 s50, s35
	s_cselect_b64 s[56:57], -1, 0
	s_and_b64 s[24:25], s[24:25], s[56:57]
	s_andn2_b64 vcc, exec, s[24:25]
	s_cbranch_vccnz .LBB0_579
	s_waitcnt vmcnt(8)
	v_mfma_f32_16x16x32_bf16 v[166:169], v[102:105], v[62:65], 0
	v_mfma_f32_16x16x32_bf16 v[170:173], v[106:109], v[58:61], v[166:169]
	v_mfma_f32_16x16x32_bf16 v[166:169], v[110:113], v[62:65], 0
	v_mfma_f32_16x16x32_bf16 v[166:169], v[114:117], v[58:61], v[166:169]
	ds_read_b32 v210, v218 offset:620
	ds_read_b32 v211, v219 offset:620
	ds_read_b32 v212, v220 offset:620
	ds_read_b32 v213, v221 offset:620
	ds_read_b32 v214, v222 offset:620
	ds_read_b32 v215, v223 offset:620
	ds_read_b32 v216, v224 offset:620
	ds_read_b32 v217, v225 offset:620
	s_waitcnt lgkmcnt(0)
	v_add_f32_e32 v210, v170, v210
	v_add_f32_e32 v211, v166, v211
	v_add_f32_e32 v212, v171, v212
	v_add_f32_e32 v213, v167, v213
	v_add_f32_e32 v214, v172, v214
	v_add_f32_e32 v215, v168, v215
	v_add_f32_e32 v216, v173, v216
	v_add_f32_e32 v217, v169, v217
	v_cndmask_b32_e64 v186, v19, v210, s[6:7]
	v_cndmask_b32_e64 v170, v19, v211, s[8:9]
	v_cndmask_b32_e64 v166, v19, v212, s[10:11]
	v_cndmask_b32_e64 v171, v19, v213, s[14:15]
	v_cndmask_b32_e64 v167, v19, v214, s[16:17]
	v_cndmask_b32_e64 v172, v19, v215, s[18:19]
	v_cndmask_b32_e64 v168, v19, v216, s[20:21]
	v_cndmask_b32_e64 v173, v19, v217, s[2:3]
	v_max_f32_e32 v169, v186, v166
	v_max_f32_e32 v187, v167, v168
	v_max_f32_e32 v203, v172, v173
	v_max3_f32 v203, v170, v171, v203
	v_max3_f32 v169, v169, v187, v203
	v_mov_b32_e32 v187, v169
	s_nop 1
	v_permlane16_swap_b32 v187, v169
	s_nop 1
	s_nop 0
	v_max_f32_e32 v169, v187, v169
	v_mov_b32_e32 v187, v169
	s_nop 1
	v_permlane32_swap_b32 v187, v169
	s_nop 1
	s_nop 0
	v_max3_f32 v187, v201, v187, v169
	v_cmp_gt_f32_e32 vcc, v187, v201
	s_cbranch_vccz .LBB0_577
	v_sub_f32_e32 v169, v201, v187
	v_mul_f32_e32 v169, v20, v169
	v_exp_f32_e32 v204, v169
	s_nop 0
	v_mul_f32_e32 v0, v0, v204
	v_pk_mul_f32 v[36:37], v[36:37], v[204:205] op_sel_hi:[1,0]
	v_pk_mul_f32 v[34:35], v[34:35], v[204:205] op_sel_hi:[1,0]
	v_pk_mul_f32 v[32:33], v[32:33], v[204:205] op_sel_hi:[1,0]
	v_pk_mul_f32 v[30:31], v[30:31], v[204:205] op_sel_hi:[1,0]
	v_pk_mul_f32 v[28:29], v[28:29], v[204:205] op_sel_hi:[1,0]
	v_pk_mul_f32 v[26:27], v[26:27], v[204:205] op_sel_hi:[1,0]
	v_pk_mul_f32 v[24:25], v[24:25], v[204:205] op_sel_hi:[1,0]
	v_pk_mul_f32 v[22:23], v[22:23], v[204:205] op_sel_hi:[1,0]
	s_branch .LBB0_578

; __device__ __forceinline__ float qmax(float x) { float a = x, b = x; swap16(a, b); a = fmaxf(a, b); b = a; swap32(a, b); return fmaxf(a, b); }
; __device__ __forceinline__ void softmax_pv(float& m, float& l, f32x4 (&o)[4], f32x4 s0, f32x4 s1, const bf16x8 (&vf)[4], float kL2e) {
;     float mx = fmaxf(fmaxf(fmaxf(s0[0], s0[1]), fmaxf(s0[2], s0[3])), fmaxf(fmaxf(s1[0], s1[1]), fmaxf(s1[2], s1[3])));
;     mx = qmax(mx);
;     const float mn = fmaxf(m, mx);
;     if (__builtin_amdgcn_ballot_w64(mn > m) != 0ull) {
;         const float alpha = __builtin_amdgcn_exp2f((m - mn) * kL2e);
;         l *= alpha;
; #pragma unroll
;         for (int dt = 0; dt < 4; ++dt) o[dt] = o[dt] * alpha;
;         m = mn;
.LBB0_579:
	s_cmp_ge_u32 s50, s26
	s_cselect_b64 s[24:25], -1, 0
	s_cmp_lt_u32 s50, s42
	s_cselect_b64 s[56:57], -1, 0
	s_and_b64 s[24:25], s[24:25], s[56:57]
	s_andn2_b64 vcc, exec, s[24:25]
	s_cbranch_vccnz .LBB0_600
	s_waitcnt vmcnt(8)
	v_mfma_f32_16x16x32_bf16 v[166:169], v[102:105], v[50:53], 0
	v_mfma_f32_16x16x32_bf16 v[170:173], v[106:109], v[42:45], v[166:169]
	v_mfma_f32_16x16x32_bf16 v[166:169], v[110:113], v[50:53], 0
	v_mfma_f32_16x16x32_bf16 v[166:169], v[114:117], v[42:45], v[166:169]
	ds_read_b32 v210, v218 offset:496
	ds_read_b32 v211, v219 offset:496
	ds_read_b32 v212, v220 offset:496
	ds_read_b32 v213, v221 offset:496
	ds_read_b32 v214, v222 offset:496
	ds_read_b32 v215, v223 offset:496
	ds_read_b32 v216, v224 offset:496
	ds_read_b32 v217, v225 offset:496
	s_waitcnt lgkmcnt(0)
	v_add_f32_e32 v210, v170, v210
	v_add_f32_e32 v211, v166, v211
	v_add_f32_e32 v212, v171, v212
	v_add_f32_e32 v213, v167, v213
	v_add_f32_e32 v214, v172, v214
	v_add_f32_e32 v215, v168, v215
	v_add_f32_e32 v216, v173, v216
	v_add_f32_e32 v217, v169, v217
	v_cndmask_b32_e64 v186, v19, v210, s[6:7]
	v_cndmask_b32_e64 v170, v19, v211, s[8:9]
	v_cndmask_b32_e64 v166, v19, v212, s[10:11]
	v_cndmask_b32_e64 v171, v19, v213, s[14:15]
	v_cndmask_b32_e64 v167, v19, v214, s[16:17]
	v_cndmask_b32_e64 v172, v19, v215, s[18:19]
	v_cndmask_b32_e64 v168, v19, v216, s[20:21]
	v_cndmask_b32_e64 v173, v19, v217, s[2:3]
	v_max_f32_e32 v169, v186, v166
	v_max_f32_e32 v187, v167, v168
	v_max_f32_e32 v203, v172, v173
	v_max3_f32 v203, v170, v171, v203
	v_max3_f32 v169, v169, v187, v203
	v_mov_b32_e32 v187, v169
	s_nop 1
	v_permlane16_swap_b32 v169, v187
	s_nop 1
	s_nop 0
	v_max_f32_e32 v169, v169, v187
	v_mov_b32_e32 v187, v169
	s_nop 1
	v_permlane32_swap_b32 v169, v187
	s_nop 1
	s_nop 0
	v_max3_f32 v187, v202, v169, v187
	v_cmp_gt_f32_e32 vcc, v187, v202
	s_cbranch_vccz .LBB0_598
	v_sub_f32_e32 v169, v202, v187
	v_mul_f32_e32 v169, v20, v169
	v_exp_f32_e32 v202, v169
	s_nop 0
	v_mul_f32_e32 v18, v18, v202
	v_pk_mul_f32 v[16:17], v[16:17], v[202:203] op_sel_hi:[1,0]
	v_pk_mul_f32 v[14:15], v[14:15], v[202:203] op_sel_hi:[1,0]
	v_pk_mul_f32 v[12:13], v[12:13], v[202:203] op_sel_hi:[1,0]
	v_pk_mul_f32 v[10:11], v[10:11], v[202:203] op_sel_hi:[1,0]
	v_pk_mul_f32 v[8:9], v[8:9], v[202:203] op_sel_hi:[1,0]
	v_pk_mul_f32 v[6:7], v[6:7], v[202:203] op_sel_hi:[1,0]
	v_pk_mul_f32 v[4:5], v[4:5], v[202:203] op_sel_hi:[1,0]
	v_pk_mul_f32 v[2:3], v[2:3], v[202:203] op_sel_hi:[1,0]
	s_branch .LBB0_599

; __device__ __forceinline__ float qmax(float x) { float a = x, b = x; swap16(a, b); a = fmaxf(a, b); b = a; swap32(a, b); return fmaxf(a, b); }
; __device__ __forceinline__ void softmax_pv(float& m, float& l, f32x4 (&o)[4], f32x4 s0, f32x4 s1, const bf16x8 (&vf)[4], float kL2e) {
;     float mx = fmaxf(fmaxf(fmaxf(s0[0], s0[1]), fmaxf(s0[2], s0[3])), fmaxf(fmaxf(s1[0], s1[1]), fmaxf(s1[2], s1[3])));
;     mx = qmax(mx);
;     const float mn = fmaxf(m, mx);
;     if (__builtin_amdgcn_ballot_w64(mn > m) != 0ull) {
;         const float alpha = __builtin_amdgcn_exp2f((m - mn) * kL2e);
;         l *= alpha;
; #pragma unroll
;         for (int dt = 0; dt < 4; ++dt) o[dt] = o[dt] * alpha;
;         m = mn;
.LBB0_600:
	s_cmp_ge_i32 s48, s29
	s_cbranch_scc1 .LBB0_515
	s_add_i32 s24, s49, 2
	s_min_i32 s24, s24, s31
	s_add_i32 s24, s24, s1
	s_lshl_b32 s24, s24, 6
	s_add_i32 s24, s24, s30
	s_waitcnt vmcnt(10)
	v_mad_i64_i32 v[110:111], s[56:57], s24, v242, v[182:183]
	s_ashr_i32 s25, s24, 31
	v_add_co_u32_e32 v114, vcc, 0x5000, v110
	v_lshl_add_u64 v[126:127], s[24:25], 1, v[184:185]
	s_nop 0
	v_addc_co_u32_e32 v115, vcc, 0, v111, vcc
	v_add_co_u32_e32 v122, vcc, 0x90000, v126
	global_load_dwordx4 v[102:105], v[110:111], off
	global_load_dwordx4 v[106:109], v[110:111], off offset:64
	v_addc_co_u32_e32 v123, vcc, 0, v127, vcc
	v_add_co_u32_e32 v128, vcc, 0x121000, v126
	global_load_dwordx4 v[110:113], v[114:115], off offset:2048
	s_nop 0
	global_load_dwordx4 v[114:117], v[114:115], off offset:2112
	v_addc_co_u32_e32 v129, vcc, 0, v127, vcc
	v_add_co_u32_e32 v130, vcc, 0x1b1000, v126
	global_load_dwordx4 v[118:121], v[126:127], off
	s_nop 0
	global_load_dwordx4 v[122:125], v[122:123], off offset:2048
	v_addc_co_u32_e32 v131, vcc, 0, v127, vcc
	global_load_dwordx4 v[126:129], v[128:129], off
	s_nop 0
	global_load_dwordx4 v[130:133], v[130:131], off offset:2048
	s_andn2_b64 vcc, exec, s[22:23]
	s_cbranch_vccnz .LBB0_623
	s_waitcnt vmcnt(15)
	v_mfma_f32_16x16x32_bf16 v[166:169], v[150:153], v[82:85], 0
	s_waitcnt vmcnt(14)
	v_mfma_f32_16x16x32_bf16 v[170:173], v[154:157], v[78:81], v[166:169]
	s_waitcnt vmcnt(13)
	v_mfma_f32_16x16x32_bf16 v[166:169], v[162:165], v[82:85], 0
	s_waitcnt vmcnt(12)
	v_mfma_f32_16x16x32_bf16 v[166:169], v[158:161], v[78:81], v[166:169]
	ds_read_b32 v210, v218 offset:992
	ds_read_b32 v211, v219 offset:992
	ds_read_b32 v212, v220 offset:992
	ds_read_b32 v213, v221 offset:992
	ds_read_b32 v214, v222 offset:992
	ds_read_b32 v215, v223 offset:992
	ds_read_b32 v216, v224 offset:992
	ds_read_b32 v217, v225 offset:992
	s_waitcnt lgkmcnt(0)
	v_add_f32_e32 v210, v170, v210
	v_add_f32_e32 v211, v166, v211
	v_add_f32_e32 v212, v171, v212
	v_add_f32_e32 v213, v167, v213
	v_add_f32_e32 v214, v172, v214
	v_add_f32_e32 v215, v168, v215
	v_add_f32_e32 v216, v173, v216
	v_add_f32_e32 v217, v169, v217
	v_cndmask_b32_e64 v186, v19, v210, s[6:7]
	v_cndmask_b32_e64 v170, v19, v211, s[8:9]
	v_cndmask_b32_e64 v166, v19, v212, s[10:11]
	v_cndmask_b32_e64 v171, v19, v213, s[14:15]
	v_cndmask_b32_e64 v167, v19, v214, s[16:17]
	v_cndmask_b32_e64 v172, v19, v215, s[18:19]
	v_cndmask_b32_e64 v168, v19, v216, s[20:21]
	v_cndmask_b32_e64 v173, v19, v217, s[2:3]
	v_max_f32_e32 v169, v186, v166
	v_max_f32_e32 v187, v167, v168
	v_max_f32_e32 v203, v172, v173
	v_max3_f32 v203, v170, v171, v203
	v_max3_f32 v169, v169, v187, v203
	v_mov_b32_e32 v187, v169
	s_nop 1
	v_permlane16_swap_b32 v169, v187
	s_nop 1
	s_nop 0
	v_max_f32_e32 v169, v169, v187
	v_mov_b32_e32 v187, v169
	s_nop 1
	v_permlane32_swap_b32 v169, v187
	s_nop 1
	s_nop 0
	v_max3_f32 v187, v199, v169, v187
	v_cmp_gt_f32_e32 vcc, v187, v199
	s_cbranch_vccz .LBB0_621
	v_sub_f32_e32 v169, v199, v187
	v_mul_f32_e32 v169, v20, v169
	v_exp_f32_e32 v204, v169
	s_nop 0
	v_mul_f32_e32 v190, v190, v204
	v_pk_mul_f32 v[100:101], v[100:101], v[204:205] op_sel_hi:[1,0]
	v_pk_mul_f32 v[98:99], v[98:99], v[204:205] op_sel_hi:[1,0]
	v_pk_mul_f32 v[96:97], v[96:97], v[204:205] op_sel_hi:[1,0]
	v_pk_mul_f32 v[94:95], v[94:95], v[204:205] op_sel_hi:[1,0]
	v_pk_mul_f32 v[92:93], v[92:93], v[204:205] op_sel_hi:[1,0]
	v_pk_mul_f32 v[90:91], v[90:91], v[204:205] op_sel_hi:[1,0]
	v_pk_mul_f32 v[88:89], v[88:89], v[204:205] op_sel_hi:[1,0]
	v_pk_mul_f32 v[86:87], v[86:87], v[204:205] op_sel_hi:[1,0]
	s_branch .LBB0_622

; __device__ __forceinline__ float qmax(float x) { float a = x, b = x; swap16(a, b); a = fmaxf(a, b); b = a; swap32(a, b); return fmaxf(a, b); }
; __device__ __forceinline__ void softmax_pv(float& m, float& l, f32x4 (&o)[4], f32x4 s0, f32x4 s1, const bf16x8 (&vf)[4], float kL2e) {
;     float mx = fmaxf(fmaxf(fmaxf(s0[0], s0[1]), fmaxf(s0[2], s0[3])), fmaxf(fmaxf(s1[0], s1[1]), fmaxf(s1[2], s1[3])));
;     mx = qmax(mx);
;     const float mn = fmaxf(m, mx);
;     if (__builtin_amdgcn_ballot_w64(mn > m) != 0ull) {
;         const float alpha = __builtin_amdgcn_exp2f((m - mn) * kL2e);
;         l *= alpha;
; #pragma unroll
;         for (int dt = 0; dt < 4; ++dt) o[dt] = o[dt] * alpha;
;         m = mn;
.LBB0_623:
	s_add_i32 s50, s50, 1
	s_cmp_ge_u32 s50, s27
	s_cselect_b64 s[22:23], -1, 0
	s_cmp_lt_u32 s50, s34
	s_cselect_b64 s[24:25], -1, 0
	s_and_b64 s[22:23], s[22:23], s[24:25]
	s_andn2_b64 vcc, exec, s[22:23]
	s_cbranch_vccnz .LBB0_644
	s_waitcnt vmcnt(15)
	v_mfma_f32_16x16x32_bf16 v[166:169], v[150:153], v[74:77], 0
	s_waitcnt vmcnt(14)
	v_mfma_f32_16x16x32_bf16 v[170:173], v[154:157], v[70:73], v[166:169]
	s_waitcnt vmcnt(13)
	v_mfma_f32_16x16x32_bf16 v[166:169], v[162:165], v[74:77], 0
	s_waitcnt vmcnt(12)
	v_mfma_f32_16x16x32_bf16 v[166:169], v[158:161], v[70:73], v[166:169]
	ds_read_b32 v210, v218 offset:868
	ds_read_b32 v211, v219 offset:868
	ds_read_b32 v212, v220 offset:868
	ds_read_b32 v213, v221 offset:868
	ds_read_b32 v214, v222 offset:868
	ds_read_b32 v215, v223 offset:868
	ds_read_b32 v216, v224 offset:868
	ds_read_b32 v217, v225 offset:868
	s_waitcnt lgkmcnt(0)
	v_add_f32_e32 v210, v170, v210
	v_add_f32_e32 v211, v166, v211
	v_add_f32_e32 v212, v171, v212
	v_add_f32_e32 v213, v167, v213
	v_add_f32_e32 v214, v172, v214
	v_add_f32_e32 v215, v168, v215
	v_add_f32_e32 v216, v173, v216
	v_add_f32_e32 v217, v169, v217
	v_cndmask_b32_e64 v186, v19, v210, s[6:7]
	v_cndmask_b32_e64 v170, v19, v211, s[8:9]
	v_cndmask_b32_e64 v166, v19, v212, s[10:11]
	v_cndmask_b32_e64 v171, v19, v213, s[14:15]
	v_cndmask_b32_e64 v167, v19, v214, s[16:17]
	v_cndmask_b32_e64 v172, v19, v215, s[18:19]
	v_cndmask_b32_e64 v168, v19, v216, s[20:21]
	v_cndmask_b32_e64 v173, v19, v217, s[2:3]
	v_max_f32_e32 v169, v186, v166
	v_max_f32_e32 v187, v167, v168
	v_max_f32_e32 v203, v172, v173
	v_max3_f32 v203, v170, v171, v203
	v_max3_f32 v169, v169, v187, v203
	v_mov_b32_e32 v187, v169
	s_nop 1
	v_permlane16_swap_b32 v169, v187
	s_nop 1
	s_nop 0
	v_max_f32_e32 v169, v169, v187
	v_mov_b32_e32 v187, v169
	s_nop 1
	v_permlane32_swap_b32 v169, v187
	s_nop 1
	s_nop 0
	v_max3_f32 v187, v200, v169, v187
	v_cmp_gt_f32_e32 vcc, v187, v200
	s_cbranch_vccz .LBB0_642
	v_sub_f32_e32 v169, v200, v187
	v_mul_f32_e32 v169, v20, v169
	v_exp_f32_e32 v200, v169
	s_nop 0
	v_mul_f32_e32 v189, v189, v200
	v_pk_mul_f32 v[68:69], v[68:69], v[200:201] op_sel_hi:[1,0]
	v_pk_mul_f32 v[66:67], v[66:67], v[200:201] op_sel_hi:[1,0]
	v_pk_mul_f32 v[56:57], v[56:57], v[200:201] op_sel_hi:[1,0]
	v_pk_mul_f32 v[54:55], v[54:55], v[200:201] op_sel_hi:[1,0]
	v_pk_mul_f32 v[48:49], v[48:49], v[200:201] op_sel_hi:[1,0]
	v_pk_mul_f32 v[46:47], v[46:47], v[200:201] op_sel_hi:[1,0]
	v_pk_mul_f32 v[40:41], v[40:41], v[200:201] op_sel_hi:[1,0]
	v_pk_mul_f32 v[38:39], v[38:39], v[200:201] op_sel_hi:[1,0]
	s_branch .LBB0_643

; __device__ __forceinline__ float qmax(float x) { float a = x, b = x; swap16(a, b); a = fmaxf(a, b); b = a; swap32(a, b); return fmaxf(a, b); }
; __device__ __forceinline__ void softmax_pv(float& m, float& l, f32x4 (&o)[4], f32x4 s0, f32x4 s1, const bf16x8 (&vf)[4], float kL2e) {
;     float mx = fmaxf(fmaxf(fmaxf(s0[0], s0[1]), fmaxf(s0[2], s0[3])), fmaxf(fmaxf(s1[0], s1[1]), fmaxf(s1[2], s1[3])));
;     mx = qmax(mx);
;     const float mn = fmaxf(m, mx);
;     if (__builtin_amdgcn_ballot_w64(mn > m) != 0ull) {
;         const float alpha = __builtin_amdgcn_exp2f((m - mn) * kL2e);
;         l *= alpha;
; #pragma unroll
;         for (int dt = 0; dt < 4; ++dt) o[dt] = o[dt] * alpha;
;         m = mn;
.LBB0_644:
	s_cmp_ge_u32 s50, s28
	s_cselect_b64 s[22:23], -1, 0
	s_cmp_lt_u32 s50, s35
	s_cselect_b64 s[24:25], -1, 0
	s_and_b64 s[22:23], s[22:23], s[24:25]
	s_andn2_b64 vcc, exec, s[22:23]
	s_cbranch_vccnz .LBB0_665
	s_waitcnt vmcnt(15)
	v_mfma_f32_16x16x32_bf16 v[166:169], v[150:153], v[62:65], 0
	s_waitcnt vmcnt(14)
	v_mfma_f32_16x16x32_bf16 v[170:173], v[154:157], v[58:61], v[166:169]
	s_waitcnt vmcnt(13)
	v_mfma_f32_16x16x32_bf16 v[166:169], v[162:165], v[62:65], 0
	s_waitcnt vmcnt(12)
	v_mfma_f32_16x16x32_bf16 v[166:169], v[158:161], v[58:61], v[166:169]
	ds_read_b32 v210, v218 offset:744
	ds_read_b32 v211, v219 offset:744
	ds_read_b32 v212, v220 offset:744
	ds_read_b32 v213, v221 offset:744
	ds_read_b32 v214, v222 offset:744
	ds_read_b32 v215, v223 offset:744
	ds_read_b32 v216, v224 offset:744
	ds_read_b32 v217, v225 offset:744
	s_waitcnt lgkmcnt(0)
	v_add_f32_e32 v210, v170, v210
	v_add_f32_e32 v211, v166, v211
	v_add_f32_e32 v212, v171, v212
	v_add_f32_e32 v213, v167, v213
	v_add_f32_e32 v214, v172, v214
	v_add_f32_e32 v215, v168, v215
	v_add_f32_e32 v216, v173, v216
	v_add_f32_e32 v217, v169, v217
	v_cndmask_b32_e64 v186, v19, v210, s[6:7]
	v_cndmask_b32_e64 v170, v19, v211, s[8:9]
	v_cndmask_b32_e64 v166, v19, v212, s[10:11]
	v_cndmask_b32_e64 v171, v19, v213, s[14:15]
	v_cndmask_b32_e64 v167, v19, v214, s[16:17]
	v_cndmask_b32_e64 v172, v19, v215, s[18:19]
	v_cndmask_b32_e64 v168, v19, v216, s[20:21]
	v_cndmask_b32_e64 v173, v19, v217, s[2:3]
	v_max_f32_e32 v169, v186, v166
	v_max_f32_e32 v187, v167, v168
	v_max_f32_e32 v203, v172, v173
	v_max3_f32 v203, v170, v171, v203
	v_max3_f32 v169, v169, v187, v203
	v_mov_b32_e32 v187, v169
	s_nop 1
	v_permlane16_swap_b32 v169, v187
	s_nop 1
	s_nop 0
	v_max_f32_e32 v169, v169, v187
	v_mov_b32_e32 v187, v169
	s_nop 1
	v_permlane32_swap_b32 v169, v187
	s_nop 1
	s_nop 0
	v_max3_f32 v187, v201, v169, v187
	v_cmp_gt_f32_e32 vcc, v187, v201
	s_cbranch_vccz .LBB0_663
	v_sub_f32_e32 v169, v201, v187
	v_mul_f32_e32 v169, v20, v169
	v_exp_f32_e32 v204, v169
	s_nop 0
	v_mul_f32_e32 v0, v0, v204
	v_pk_mul_f32 v[36:37], v[36:37], v[204:205] op_sel_hi:[1,0]
	v_pk_mul_f32 v[34:35], v[34:35], v[204:205] op_sel_hi:[1,0]
	v_pk_mul_f32 v[32:33], v[32:33], v[204:205] op_sel_hi:[1,0]
	v_pk_mul_f32 v[30:31], v[30:31], v[204:205] op_sel_hi:[1,0]
	v_pk_mul_f32 v[28:29], v[28:29], v[204:205] op_sel_hi:[1,0]
	v_pk_mul_f32 v[26:27], v[26:27], v[204:205] op_sel_hi:[1,0]
	v_pk_mul_f32 v[24:25], v[24:25], v[204:205] op_sel_hi:[1,0]
	v_pk_mul_f32 v[22:23], v[22:23], v[204:205] op_sel_hi:[1,0]
	s_branch .LBB0_664

.LBB0_665:
	s_cmp_lt_u32 s50, s26
	s_cbranch_scc1 .LBB0_515
	s_waitcnt vmcnt(15)
	v_mfma_f32_16x16x32_bf16 v[150:153], v[150:153], v[50:53], 0
	s_waitcnt vmcnt(14)
	v_mfma_f32_16x16x32_bf16 v[154:157], v[154:157], v[42:45], v[150:153]
	s_waitcnt vmcnt(13)
	v_mfma_f32_16x16x32_bf16 v[150:153], v[162:165], v[50:53], 0
	s_waitcnt vmcnt(12)
	v_mfma_f32_16x16x32_bf16 v[150:153], v[158:161], v[42:45], v[150:153]
	ds_read_b32 v210, v218 offset:620
	ds_read_b32 v211, v219 offset:620
	ds_read_b32 v212, v220 offset:620
	ds_read_b32 v213, v221 offset:620
	ds_read_b32 v214, v222 offset:620
	ds_read_b32 v215, v223 offset:620
	ds_read_b32 v216, v224 offset:620
	ds_read_b32 v217, v225 offset:620
	s_waitcnt lgkmcnt(0)
	v_add_f32_e32 v210, v154, v210
	v_add_f32_e32 v211, v150, v211
	v_add_f32_e32 v212, v155, v212
	v_add_f32_e32 v213, v151, v213
	v_add_f32_e32 v214, v156, v214
	v_add_f32_e32 v215, v152, v215
	v_add_f32_e32 v216, v157, v216
	v_add_f32_e32 v217, v153, v217
	v_cndmask_b32_e64 v162, v19, v210, s[6:7]
	v_cndmask_b32_e64 v154, v19, v211, s[8:9]
	v_cndmask_b32_e64 v150, v19, v212, s[10:11]
	v_cndmask_b32_e64 v155, v19, v213, s[14:15]
	v_cndmask_b32_e64 v151, v19, v214, s[16:17]
	v_cndmask_b32_e64 v156, v19, v215, s[18:19]
	v_cndmask_b32_e64 v152, v19, v216, s[20:21]
	v_cndmask_b32_e64 v157, v19, v217, s[2:3]
	s_branch .LBB0_512
